# walk block loops: branchless selection of the ring slot's block index
# baseline (speedup 1.0000x reference)
.LBB0_1255:
	s_cmpk_eq_u32 s15, 0x8000
	s_cselect_b32 s21, s12, s16
	s_cmp_eq_u32 s17, 1
	s_cselect_b32 s21, s14, s21
	s_cmp_lt_i32 s17, 1
	s_cselect_b32 s21, s10, s21

.LBB0_1403:
	s_cmpk_eq_u32 s13, 0x8000
	s_cselect_b32 s6, s10, s14
	s_cmp_eq_u32 s15, 1
	s_cselect_b32 s6, s12, s6
	s_cmp_lt_i32 s15, 1
	s_cselect_b32 s6, s8, s6
